# XCD-local barrier: the 5 seams per layer whose producer/consumer tiles stay on one XCD skip the L2 writeback + cross-XCD level when a runtime census proves logical group == physical XCC
# speedup vs baseline: 1.0174x; 1.0173x over previous
; #define LAS __attribute__((address_space(3)))
; __device__ __forceinline__ unsigned xb_add(unsigned* p, unsigned v) { return __hip_atomic_fetch_add(p, v, __ATOMIC_RELAXED, __HIP_MEMORY_SCOPE_AGENT); }
; __device__ __forceinline__ unsigned xb_xcc_id() { return (unsigned)__builtin_amdgcn_s_getreg((3 << 11) | 20) & 0xFu; }
; #define XB_T0(w) ((w) == 0 && pg8::lane_id_opaque() == 0)
; __device__ __forceinline__ XcdBarrier xcd_barrier_post(unsigned* bar, volatile LAS unsigned* st, int wid) {
;     XcdBarrier b; b.bar = bar; b.x = xb_xcc_id(); b.st = st; b.wid = wid;
;     if (XB_T0(wid)) (void)xb_add(&bar[XB_XCNT(b.x)], 1u);
;     return b;
; }
.LBB0_4:
	v_readlane_b32 s0, v254, 0
	v_readlane_b32 s1, v254, 1
	s_load_dwordx2 s[64:65], s[0:1], 0x98
	v_cndmask_b32_e64 v2, 0, 1, s[4:5]
	v_cmp_ne_u32_e64 s[0:1], 1, v2
	s_waitcnt lgkmcnt(0)
	s_barrier
	s_getreg_b32 s6, hwreg(HW_REG_XCC_ID, 0, 4)
	s_add_u32 s2, s64, 0x4000
	v_writelane_b32 v254, s0, 2
	s_addc_u32 s3, s65, 0
	s_andn2_b64 vcc, exec, s[4:5]
	v_writelane_b32 v254, s1, 3
	s_and_b32 s12, s6, 15
	s_cbranch_vccnz .LBB0_9
	v_mov_b32_e32 v2, 0
	s_nop 0
	v_mbcnt_lo_u32_b32 v2, -1, v2
	v_mbcnt_hi_u32_b32 v2, -1, v2
	v_cmp_eq_u32_e32 vcc, 0, v2
	s_and_saveexec_b64 s[4:5], vcc
	s_cbranch_execz .LBB0_8
	s_mov_b64 s[6:7], exec
	v_mbcnt_lo_u32_b32 v2, s6, 0
	v_mbcnt_hi_u32_b32 v2, s7, v2
	v_cmp_eq_u32_e32 vcc, 0, v2
	s_and_b64 s[8:9], exec, vcc
	s_mov_b64 exec, s[8:9]
	s_cbranch_execz .LBB0_8
	s_lshl_b32 s8, s12, 8
	s_bcnt1_i32_b64 s6, s[6:7]
	v_mov_b32_e32 v2, s8
	v_mov_b32_e32 v3, s6
	global_atomic_add v2, v3, s[2:3] offset:1024
	s_lshl_b32 s8, s97, 2
	s_add_i32 s8, s8, 0x4000
	s_add_i32 s6, s12, 1
	v_mov_b32_e32 v4, s8
	v_mov_b32_e32 v5, s6
	global_store_dword v4, v5, s[2:3] sc1

; __device__ __forceinline__ unsigned xb_ld(unsigned* p)              { return __hip_atomic_load(p, __ATOMIC_RELAXED, __HIP_MEMORY_SCOPE_AGENT); }
; __device__ __forceinline__ void xcd_barrier_complete(unsigned* bar, unsigned x, unsigned& nloc, unsigned& nx) {
;     const unsigned G = gridDim.x * gridDim.y * gridDim.z;
;     unsigned sum, cnt, mine, sp = 0u;
;     for (;;) {
;         sum = 0u; cnt = 0u; mine = 0u;
; #pragma unroll
;         for (unsigned j = 0; j < 16; ++j) { const unsigned c = xb_ld(&bar[XB_XCNT(j)]); sum += c; cnt += (c > 0u) ? 1u : 0u; mine = (j == x) ? c : mine; }
;         if (sum == G) break;
;         __builtin_amdgcn_s_sleep(1);
;         if ((++sp & 255u) == 0u) { if (xb_ld(&bar[XB_TMO])) break; if (sp > XB_SPIN_CAP) { atomicAdd(&bar[XB_TMO], 1u); break; } }
;     }
;     nloc = mine > 0u ? mine : 1u; nx = cnt > 0u ? cnt : 1u;
; }
.LBB0_122:
	v_mbcnt_lo_u32_b32 v0, -1, 0
	v_mbcnt_hi_u32_b32 v0, -1, v0
	v_and_b32_e32 v2, 7, v0
	v_lshlrev_b32_e32 v1, 2, v0
	v_lshlrev_b32_e32 v2, 2, v2
	s_add_u32 s20, s64, 0x8000
	s_addc_u32 s21, s65, 0
	global_load_dword v3, v1, s[20:21] sc1
	global_load_dword v4, v1, s[20:21] offset:256 sc1
	global_load_dword v5, v1, s[20:21] offset:512 sc1
	global_load_dword v6, v1, s[20:21] offset:768 sc1
	global_load_dword v2, v2, s[20:21] sc1
	s_waitcnt vmcnt(0)
	v_xor_b32_e32 v3, v3, v2
	v_xor_b32_e32 v4, v4, v2
	v_xor_b32_e32 v5, v5, v2
	v_xor_b32_e32 v6, v6, v2
	v_or3_b32 v3, v3, v4, v5
	v_or_b32_e32 v3, v3, v6
	v_lshlrev_b32_e64 v4, v2, 1
	v_cmp_ne_u32_e32 vcc, 0, v3
	s_nop 1
	v_readlane_b32 s14, v4, 0
	v_readlane_b32 s15, v4, 1
	v_readlane_b32 s20, v4, 2
	v_readlane_b32 s21, v4, 3
	s_or_b32 s14, s14, s15
	s_or_b32 s20, s20, s21
	s_or_b32 s14, s14, s20
	v_readlane_b32 s15, v4, 4
	v_readlane_b32 s20, v4, 5
	v_readlane_b32 s21, v4, 6
	s_or_b32 s14, s14, s15
	s_or_b32 s20, s20, s21
	s_or_b32 s14, s14, s20
	v_readlane_b32 s15, v4, 7
	s_nop 0
	s_or_b32 s14, s14, s15
	s_and_b64 vcc, vcc, exec
	s_cselect_b32 s20, 0, 1
	s_bcnt1_i32_b32 s15, s14
	s_cmp_eq_u32 s15, 8
	s_cselect_b32 s15, 1, 0
	s_and_b32 s20, s20, s15
	s_and_b32 s15, s14, 1
	s_cmp_eq_u32 s15, 0
	s_cselect_b32 s15, 1, 0
	s_and_b32 s20, s20, s15
	s_cmp_eq_u32 s46, 0x100
	s_cselect_b32 s15, 1, 0
	s_and_b32 s20, s20, s15
	s_cmp_eq_u32 s66, 0
	s_cselect_b32 s15, 1, 0
	s_and_b32 s20, s20, s15
	s_and_b32 s9, s13, 0xffffffc0
	s_ashr_i32 s17, s46, 31
	s_add_u32 s44, s64, 0x4200
	s_addc_u32 s45, s65, 0
	s_add_u32 s88, s64, 0x4400
	s_addc_u32 s89, s65, 0
	s_add_u32 s90, s64, 0x4500
	s_addc_u32 s91, s65, 0
	s_add_u32 s92, s64, 0x4600
	s_addc_u32 s93, s65, 0
	s_add_u32 s76, s64, 0x4700
	s_addc_u32 s77, s65, 0
	s_add_u32 s70, s64, 0x4800
	s_addc_u32 s71, s65, 0
	s_add_u32 s72, s64, 0x4900
	s_mul_i32 s4, s33, s47
	s_addc_u32 s73, s65, 0
	s_mul_i32 s26, s4, s46
	s_add_u32 s4, s64, 0x4a00
	s_addc_u32 s5, s65, 0
	v_writelane_b32 v254, s4, 8
	s_mov_b32 s23, 0
	v_mov_b32_e32 v193, 0
	v_writelane_b32 v254, s5, 9
	s_add_u32 s4, s64, 0x4b00
	s_addc_u32 s5, s65, 0
	v_writelane_b32 v254, s4, 10
	s_mov_b32 s59, 0xf800000
	v_mov_b32_e32 v216, 1
	v_writelane_b32 v254, s5, 11
	s_add_u32 s4, s64, 0x4c00
	s_addc_u32 s5, s65, 0
	v_writelane_b32 v254, s4, 12
	v_mov_b32_e32 v217, 0x358637bd
	v_mov_b32_e32 v218, 0x260
	v_writelane_b32 v254, s5, 13
	s_add_u32 s4, s64, 0x4d00
	s_addc_u32 s5, s65, 0
	v_writelane_b32 v254, s4, 14
	s_mov_b32 s13, 0x41000000
	s_movk_i32 s37, 0x7fff
	v_writelane_b32 v254, s5, 15
	s_add_u32 s4, s64, 0x4e00
	s_addc_u32 s5, s65, 0
	v_writelane_b32 v254, s4, 16
	s_mov_b32 s33, 0x7060302
	s_mov_b32 s57, 0xffff0000
	v_writelane_b32 v254, s5, 17
	s_add_u32 s4, s64, 0x4f00
	s_addc_u32 s5, s65, 0
	v_writelane_b32 v254, s4, 18
	s_movk_i32 s47, 0x1600
	s_mov_b64 s[28:29], 0x40000
	v_writelane_b32 v254, s5, 19
	s_add_u32 s4, s64, 0x5000
	s_addc_u32 s5, s65, 0
	v_writelane_b32 v254, s4, 20
	s_mov_b64 s[30:31], 0x80
	s_mov_b64 s[34:35], 0x100
	v_writelane_b32 v254, s5, 21
	s_add_u32 s4, s64, 0x5100
	s_addc_u32 s5, s65, 0
	v_writelane_b32 v254, s4, 22
	s_mov_b32 s36, 0x3e6d3388
	s_mov_b32 s8, 0x3f35f0e3
	v_writelane_b32 v254, s5, 23
	s_add_u32 s4, s64, 0x5200
	s_addc_u32 s5, s65, 0
	v_writelane_b32 v254, s4, 24
	s_mov_b32 s24, 0xbe11a98e
	s_mov_b32 s56, 0x3e027906
	v_writelane_b32 v254, s5, 25
	s_add_u32 s4, s64, 0x5300
	s_addc_u32 s5, s65, 0
	v_writelane_b32 v254, s4, 26
	s_cmp_eq_u32 s12, 15
	s_mov_b32 s58, 0xbf38aa3b
	v_writelane_b32 v254, s5, 27
	s_cselect_b64 s[4:5], -1, 0
	v_writelane_b32 v254, s4, 28
	s_cmp_eq_u32 s12, 14
	s_mov_b64 s[60:61], 0x20000
	v_writelane_b32 v254, s5, 29
	s_cselect_b64 s[4:5], -1, 0
	v_writelane_b32 v254, s4, 30
	s_cmp_eq_u32 s12, 13
	s_mov_b64 s[62:63], 0x10000
	v_writelane_b32 v254, s5, 31
	s_cselect_b64 s[4:5], -1, 0
	v_writelane_b32 v254, s4, 32
	s_cmp_eq_u32 s12, 12
	s_mov_b64 s[48:49], 0x180
	v_writelane_b32 v254, s5, 33
	s_cselect_b64 s[4:5], -1, 0
	v_writelane_b32 v254, s4, 34
	s_cmp_eq_u32 s12, 11
	s_mov_b64 s[50:51], 0x30000
	v_writelane_b32 v254, s5, 35
	s_cselect_b64 s[4:5], -1, 0
	v_writelane_b32 v254, s4, 36
	s_cmp_eq_u32 s12, 10
	s_mov_b64 s[52:53], 0x200
	v_writelane_b32 v254, s5, 37
	s_cselect_b64 s[4:5], -1, 0
	v_writelane_b32 v254, s4, 38
	s_cmp_eq_u32 s12, 9
	s_mov_b64 s[54:55], 0x11850000
	v_writelane_b32 v254, s5, 39
	s_cselect_b64 s[4:5], -1, 0
	v_writelane_b32 v254, s4, 40
	s_cmp_eq_u32 s12, 8
	s_mov_b64 s[18:19], 0x13800280
	v_writelane_b32 v254, s5, 41
	s_cselect_b64 s[4:5], -1, 0
	v_writelane_b32 v254, s4, 42
	s_cmp_eq_u32 s12, 7
	s_nop 0
	v_writelane_b32 v254, s5, 43
	s_cselect_b64 s[4:5], -1, 0
	v_writelane_b32 v254, s4, 44
	s_cmp_eq_u32 s12, 6
	s_nop 0
	v_writelane_b32 v254, s5, 45
	s_cselect_b64 s[4:5], -1, 0
	v_writelane_b32 v254, s4, 46
	s_cmp_eq_u32 s12, 5
	s_mov_b32 s16, 0x3b000000
	v_writelane_b32 v254, s5, 47
	s_cselect_b64 s[4:5], -1, 0
	v_writelane_b32 v254, s4, 48
	s_cmp_eq_u32 s12, 4
	s_mov_b32 s68, s23
	v_writelane_b32 v254, s5, 49
	s_cselect_b64 s[4:5], -1, 0
	v_writelane_b32 v254, s4, 50
	s_cmp_eq_u32 s12, 3
	s_nop 0
	v_writelane_b32 v254, s5, 51
	s_cselect_b64 s[4:5], -1, 0
	v_writelane_b32 v254, s4, 52
	s_cmp_eq_u32 s12, 2
	s_nop 0
	v_writelane_b32 v254, s5, 53
	s_cselect_b64 s[4:5], -1, 0
	v_writelane_b32 v254, s4, 54
	s_cmp_eq_u32 s12, 1
	s_nop 0
	v_writelane_b32 v254, s5, 55
	s_cselect_b64 s[4:5], -1, 0
	v_writelane_b32 v254, s4, 56
	s_cmp_eq_u32 s12, 0
	s_nop 0
	v_writelane_b32 v254, s5, 57
	s_cselect_b64 s[4:5], -1, 0
	v_writelane_b32 v254, s4, 58
	s_nop 1
	v_writelane_b32 v254, s5, 59
	s_lshl_b32 s4, s12, 8
	s_add_u32 s2, s2, s4
	s_addc_u32 s3, s3, 0
	s_add_u32 s4, s2, 0x1400
	s_addc_u32 s5, s3, 0
	v_writelane_b32 v254, s4, 60
	s_add_u32 s2, s2, 0x2400
	s_addc_u32 s3, s3, 0
	v_writelane_b32 v254, s5, 61
	v_writelane_b32 v254, s2, 62
	s_mov_b32 s12, 0x3f07dc22
	s_nop 0
	v_writelane_b32 v254, s3, 63
	s_add_u32 s2, s64, 0x7400
	s_addc_u32 s3, s65, 0
	v_writelane_b32 v255, s2, 0
	s_nop 1
	v_writelane_b32 v255, s3, 1
	s_add_u32 s2, s64, 0x7500
	s_addc_u32 s3, s65, 0
	v_writelane_b32 v255, s2, 2
	s_nop 1
	v_writelane_b32 v255, s3, 3
	s_and_b32 s2, s46, 7
	s_cmp_eq_u32 s2, 0
	s_cselect_b64 s[2:3], -1, 0
	v_writelane_b32 v255, s2, 4
	s_nop 1
	v_writelane_b32 v255, s3, 5
	s_ashr_i32 s2, s46, 3
	s_cmpk_eq_i32 s46, 0x100
	v_writelane_b32 v255, s2, 6
	s_cselect_b64 s[2:3], -1, 0
	v_writelane_b32 v255, s2, 7
	s_cmpk_lg_i32 s46, 0x100
	s_nop 0
	v_writelane_b32 v255, s3, 8
	s_cselect_b64 s[2:3], -1, 0
	v_writelane_b32 v255, s2, 9
	s_nop 1
	v_writelane_b32 v255, s3, 10
	s_lshl_b32 s2, s46, 5
	v_writelane_b32 v255, s2, 11
	s_add_i32 s2, 0, 0x20400
	v_writelane_b32 v255, s2, 12
	s_add_i32 s2, 0, 0x20404
	v_writelane_b32 v255, s2, 13
	v_readlane_b32 s2, v254, 0
	v_readlane_b32 s3, v254, 1
	s_load_dwordx2 s[4:5], s[2:3], 0x88
	s_load_dwordx8 s[80:87], s[2:3], 0x30
	s_waitcnt lgkmcnt(0)
; #define LAS __attribute__((address_space(3)))
; #define XB_T0(w) ((w) == 0 && pg8::lane_id_opaque() == 0)
; __global__ void __launch_bounds__(512, 2) mk_fwd(Args args) {
;     ...
;     const float* x = args.in[0]; float* out = args.out;
;     ...
;     cg::grid_group grid = cg::this_grid();
;     volatile LAS unsigned* misc = (volatile LAS unsigned*)(lds + 131072 + 1024);
;     if (XB_T0(wid)) { misc[0] = 0u; misc[1] = 0u; }
;     __syncthreads();
;     XcdBarrier bar = xcd_barrier_post((unsigned*)args.ws + 4096, misc, wid);
;     const int lo = args.ph_lo, hi = args.ph_hi;
	v_writelane_b32 v255, s4, 14
	s_nop 1
	v_writelane_b32 v255, s5, 15
	s_mov_b64 s[4:5], 0
	v_writelane_b32 v255, s4, 16
	s_nop 1
	v_writelane_b32 v255, s5, 17
	s_load_dwordx2 s[4:5], s[2:3], 0x68
	s_waitcnt lgkmcnt(0)
	v_writelane_b32 v255, s4, 18
	s_nop 1
	v_writelane_b32 v255, s5, 19
	s_load_dwordx4 s[4:7], s[2:3], 0x50
	s_waitcnt lgkmcnt(0)
	v_writelane_b32 v255, s4, 20
	s_nop 1
	v_writelane_b32 v255, s5, 21
	v_writelane_b32 v255, s6, 22
	v_writelane_b32 v255, s7, 23
	s_load_dwordx4 s[4:7], s[2:3], 0x18
	s_waitcnt lgkmcnt(0)
	v_writelane_b32 v255, s4, 24
	s_nop 1
	v_writelane_b32 v255, s5, 25
	v_writelane_b32 v255, s6, 26
	v_writelane_b32 v255, s7, 27
	v_writelane_b32 v255, s80, 28
	s_nop 1
	v_writelane_b32 v255, s81, 29
	v_writelane_b32 v255, s82, 30
	v_writelane_b32 v255, s83, 31
	v_writelane_b32 v255, s84, 32
	v_writelane_b32 v255, s85, 33
	v_writelane_b32 v255, s86, 34
	v_writelane_b32 v255, s87, 35
	v_writelane_b32 v255, s96, 36
	v_writelane_b32 v255, s26, 37
	v_writelane_b32 v255, s44, 38
	s_nop 1
	v_writelane_b32 v255, s45, 39
	v_writelane_b32 v255, s88, 40
	s_nop 1
	v_writelane_b32 v255, s89, 41
	v_writelane_b32 v255, s90, 42
	s_nop 1
	v_writelane_b32 v255, s91, 43
	v_writelane_b32 v255, s92, 44
	s_nop 1
	v_writelane_b32 v255, s93, 45
	v_writelane_b32 v255, s76, 46
	s_nop 1
	v_writelane_b32 v255, s77, 47
	v_writelane_b32 v255, s70, 48
	s_nop 1
	v_writelane_b32 v255, s71, 49
	v_writelane_b32 v255, s72, 50
	s_nop 1
	v_writelane_b32 v255, s73, 51
	s_branch .LBB0_127

; __device__ __forceinline__ unsigned xb_add(unsigned* p, unsigned v) { return __hip_atomic_fetch_add(p, v, __ATOMIC_RELAXED, __HIP_MEMORY_SCOPE_AGENT); }
; __device__ __forceinline__ void xcd_barrier(const XcdBarrier& b) {
;     ...
;         if (old + 1u == (gen + 1u) * nloc) {
;             __builtin_amdgcn_fence(__ATOMIC_RELEASE, "agent");
;             asm volatile("s_waitcnt vmcnt(0)" ::: "memory");
;             const unsigned og = xb_add(&bar[XB_TOP], 1u);
;             const unsigned tg = og / nx;
;             if (og + 1u == (tg + 1u) * nx) xb_add(&bar[XB_TOPGEN], 1u);
.LBB0_433:
	s_andn2_saveexec_b64 s[2:3], s[2:3]
	s_cbranch_execz .LBB0_453
	s_mov_b64 s[2:3], exec
	s_cmp_lg_u32 s20, 0
	s_cbranch_scc0 .Lxb_full_0
	s_waitcnt vmcnt(0) lgkmcnt(0)
	buffer_inv sc1
	s_branch .Lxb_rel_0
.Lxb_full_0:
	buffer_wbl2 sc1
	s_waitcnt lgkmcnt(0)
	s_waitcnt vmcnt(0)
	v_mbcnt_lo_u32_b32 v1, s2, 0
	v_mbcnt_hi_u32_b32 v1, s3, v1
	v_cmp_eq_u32_e32 vcc, 0, v1
	s_and_saveexec_b64 s[38:39], vcc
	s_cbranch_execz .LBB0_436
	s_bcnt1_i32_b64 s2, s[2:3]
	v_mov_b32_e32 v2, s2
	v_readlane_b32 s2, v255, 0
	v_readlane_b32 s3, v255, 1
	s_nop 4
	global_atomic_add v2, v193, v2, s[2:3] sc0

; __device__ __forceinline__ unsigned xb_add(unsigned* p, unsigned v) { return __hip_atomic_fetch_add(p, v, __ATOMIC_RELAXED, __HIP_MEMORY_SCOPE_AGENT); }
; __device__ __forceinline__ void xcd_barrier(const XcdBarrier& b) {
;     ...
;             xb_add(&bar[XB_XGEN(b.x)], 1u);
;             asm volatile("s_waitcnt vmcnt(0)" ::: "memory");
.Lxb_rel_0:
	s_mov_b64 s[2:3], exec
	v_mbcnt_lo_u32_b32 v0, s2, 0
	v_mbcnt_hi_u32_b32 v0, s3, v0
	v_cmp_eq_u32_e32 vcc, 0, v0
	s_waitcnt vmcnt(0)
	s_nop 0
	s_and_saveexec_b64 s[38:39], vcc
	s_cbranch_execz .LBB0_452
	s_bcnt1_i32_b64 s2, s[2:3]
	v_mov_b32_e32 v0, s2
	v_readlane_b32 s2, v254, 62
	v_readlane_b32 s3, v254, 63
	s_nop 4
	global_atomic_add v193, v0, s[2:3]

; __device__ __forceinline__ unsigned xb_add(unsigned* p, unsigned v) { return __hip_atomic_fetch_add(p, v, __ATOMIC_RELAXED, __HIP_MEMORY_SCOPE_AGENT); }
; __device__ __forceinline__ void xcd_barrier(const XcdBarrier& b) {
;     ...
;             xb_add(&bar[XB_XGEN(b.x)], 1u);
;             asm volatile("s_waitcnt vmcnt(0)" ::: "memory");
.Lxb_rel_4:
	s_mov_b64 s[2:3], exec
	v_mbcnt_lo_u32_b32 v0, s2, 0
	v_mbcnt_hi_u32_b32 v0, s3, v0
	v_cmp_eq_u32_e32 vcc, 0, v0
	s_waitcnt vmcnt(0)
	s_nop 0
	s_and_saveexec_b64 s[38:39], vcc
	s_cbranch_execz .LBB0_123
	s_bcnt1_i32_b64 s2, s[2:3]
	v_mov_b32_e32 v0, s2
	v_readlane_b32 s2, v254, 62
	v_readlane_b32 s3, v254, 63
	s_nop 4
	global_atomic_add v193, v0, s[2:3]
	s_branch .LBB0_123
